# attention mid-stream barrier moved from MFMA step 20 to step 30
# speedup vs baseline: 1.0165x; 1.0003x over previous
.LBB0_631:
	s_add_i32 s10, s11, 1
	s_cmp_gt_i32 s11, s1
	s_cbranch_scc1 .Lattn1_stage_only
	v_add3_u32 v0, s100, v180, v229
	ds_read_b128 v[2:5], v0
	ds_read_b128 v[6:9], v0 offset:32
	ds_read_b128 v[10:13], v0 offset:64
	ds_read_b128 v[184:187], v0 offset:96
	ds_read_b128 v[188:191], v0 offset:128
	ds_read_b128 v[192:195], v0 offset:160
	ds_read_b128 v[196:199], v0 offset:192
	s_mov_b32 s16, s101
	v_add_u32_e32 v247, s16, v233
	v_add_u32_e32 v248, s16, v234
	v_add_u32_e32 v249, s16, v236
	v_add_u32_e32 v250, s16, v208
	v_add_u32_e32 v251, s16, v200
	s_cmp_lt_u32 s11, s7
	s_cselect_b64 s[16:17], -1, 0
	s_cmp_lg_u64 s[16:17], 0
	s_addc_u32 s6, s6, 0
	s_mov_b32 s22, s14
	s_mov_b32 s23, s15
	s_mov_b32 s26, s14
	s_mov_b32 s27, s15
	v_mov_b32_e32 v80, v213
	v_mov_b32_e32 v81, v80
	v_mov_b32_e32 v82, v80
	v_mov_b32_e32 v83, v80
	v_mov_b32_e32 v84, v80
	v_mov_b32_e32 v85, v80
	v_mov_b32_e32 v86, v80
	v_mov_b32_e32 v87, v80
	v_mov_b32_e32 v88, v80
	v_mov_b32_e32 v89, v80
	v_mov_b32_e32 v90, v80
	v_mov_b32_e32 v91, v80
	v_mov_b32_e32 v92, v80
	v_mov_b32_e32 v93, v80
	v_mov_b32_e32 v94, v80
	v_mov_b32_e32 v95, v80
	s_mov_b32 s11, s100
	s_waitcnt lgkmcnt(6)
	v_mfma_f32_32x32x16_bf16 v[96:111], v[2:5], v[132:135], v[80:95]
	s_mul_i32 s16, s6, 0x6000
	s_waitcnt vmcnt(4)
	ds_write_b128 v247, v[112:115]
	buffer_load_dwordx4 v[112:115], v230, s[20:23], s16 offen
	ds_read_b128 v[2:5], v0 offset:224
	s_waitcnt lgkmcnt(6)
	v_mfma_f32_32x32x16_bf16 v[96:111], v[6:9], v[136:139], v[96:111]
	ds_read_b128 v[6:9], v0 offset:256
	s_waitcnt lgkmcnt(6)
	v_mfma_f32_32x32x16_bf16 v[96:111], v[10:13], v[140:143], v[96:111]
	s_add_i32 s17, s16, 0x2000
	s_waitcnt vmcnt(4)
	ds_write_b128 v248, v[116:119]
	buffer_load_dwordx4 v[116:119], v230, s[20:23], s17 offen
	ds_read_b128 v[10:13], v0 offset:288
	s_waitcnt lgkmcnt(6)
	v_mfma_f32_32x32x16_bf16 v[96:111], v[184:187], v[144:147], v[96:111]
	ds_read_b128 v[184:187], v0 offset:320
	s_waitcnt lgkmcnt(6)
	v_mfma_f32_32x32x16_bf16 v[96:111], v[188:191], v[152:155], v[96:111]
	s_addk_i32 s16, 0x4000
	s_waitcnt vmcnt(4)
	ds_write_b128 v249, v[120:123]
	buffer_load_dwordx4 v[120:123], v230, s[20:23], s16 offen
	ds_read_b128 v[188:191], v0 offset:352
	s_waitcnt lgkmcnt(6)
	v_mfma_f32_32x32x16_bf16 v[96:111], v[192:195], v[164:167], v[96:111]
	ds_read_b128 v[192:195], v0 offset:12800
	s_waitcnt lgkmcnt(6)
	v_mfma_f32_32x32x16_bf16 v[96:111], v[196:199], v[172:175], v[96:111]
	s_lshl_b32 s16, s6, 7
	s_waitcnt vmcnt(4)
	ds_write_b128 v250, v[124:127] offset:25600
	buffer_load_dwordx4 v[124:127], v232, s[24:27], s16 offen
	ds_read_b128 v[196:199], v0 offset:12832
	s_waitcnt lgkmcnt(6)
	v_mfma_f32_32x32x16_bf16 v[96:111], v[2:5], v[160:163], v[96:111]
	ds_read_b128 v[2:5], v0 offset:12864
	s_waitcnt lgkmcnt(6)
	v_mfma_f32_32x32x16_bf16 v[96:111], v[6:9], v[148:151], v[96:111]
	s_add_i32 s16, s16, 0x100000
	s_waitcnt vmcnt(4)
	ds_write_b128 v251, v[128:131] offset:25600
	buffer_load_dwordx4 v[128:131], v232, s[24:27], s16 offen
	ds_read_b128 v[6:9], v0 offset:12896
	s_waitcnt lgkmcnt(6)
	v_mfma_f32_32x32x16_bf16 v[96:111], v[10:13], v[168:171], v[96:111]
	ds_read_b128 v[10:13], v0 offset:12928
	s_waitcnt lgkmcnt(6)
	v_mfma_f32_32x32x16_bf16 v[96:111], v[184:187], v[156:159], v[96:111]
	ds_read_b128 v[184:187], v0 offset:12960
	s_waitcnt lgkmcnt(6)
	v_mfma_f32_32x32x16_bf16 v[96:111], v[188:191], v[176:179], v[96:111]
	ds_read_b128 v[188:191], v0 offset:12992
	s_waitcnt lgkmcnt(6)
	v_mfma_f32_32x32x16_bf16 v[80:95], v[192:195], v[132:135], v[80:95]
	s_nop 8
	v_exp_f32_e32 v206, v96
	v_exp_f32_e32 v207, v97
	ds_read_b128 v[192:195], v0 offset:13024
	s_waitcnt lgkmcnt(6)
	v_mfma_f32_32x32x16_bf16 v[80:95], v[196:199], v[136:139], v[80:95]
	v_add_f32_e32 v14, v207, v206
	v_add_f32_e32 v96, v182, v14
	ds_read_b128 v[196:199], v0 offset:13056
	s_waitcnt lgkmcnt(6)
	v_mfma_f32_32x32x16_bf16 v[80:95], v[2:5], v[140:143], v[80:95]
	v_exp_f32_e32 v15, v98
	v_exp_f32_e32 v183, v99
	v_exp_f32_e32 v14, v100
	v_exp_f32_e32 v182, v101
	ds_read_b128 v[2:5], v0 offset:13088
	s_waitcnt lgkmcnt(6)
	v_mfma_f32_32x32x16_bf16 v[80:95], v[6:9], v[144:147], v[80:95]
	v_add_f32_e64 v6, v182, v14
	v_add_f32_e64 v7, v183, v15
	v_add_f32_e32 v7, v7, v96
	v_add_f32_e32 v98, v6, v7
	ds_read_b128 v[6:9], v0 offset:13120
	s_waitcnt lgkmcnt(6)
	v_mfma_f32_32x32x16_bf16 v[80:95], v[10:13], v[152:155], v[80:95]
	v_exp_f32_e32 v203, v102
	v_exp_f32_e32 v205, v103
	v_exp_f32_e32 v202, v104
	v_exp_f32_e32 v204, v105
	ds_read_b128 v[10:13], v0 offset:13152
	s_waitcnt lgkmcnt(6)
	v_mfma_f32_32x32x16_bf16 v[80:95], v[184:187], v[164:167], v[80:95]
	v_add_f32_e64 v96, v204, v202
	v_add_f32_e64 v97, v205, v203
	v_add_f32_e32 v0, v97, v98
	v_add_f32_e32 v0, v96, v0
	v_add3_u32 v209, s11, v181, v229
	ds_read_b128 v[96:99], v209 offset:25600
	s_waitcnt lgkmcnt(6)
	v_mfma_f32_32x32x16_bf16 v[80:95], v[188:191], v[172:175], v[80:95]
	v_exp_f32_e32 v187, v106
	v_exp_f32_e32 v189, v107
	v_exp_f32_e32 v186, v108
	v_exp_f32_e32 v188, v109
	ds_read_b128 v[100:103], v209 offset:30208
	s_waitcnt lgkmcnt(6)
	v_mfma_f32_32x32x16_bf16 v[80:95], v[192:195], v[160:163], v[80:95]
	v_add_f32_e64 v104, v188, v186
	v_add_f32_e64 v105, v189, v187
	v_add_f32_e32 v0, v105, v0
	v_add_f32_e32 v190, v104, v0
	ds_read_b128 v[104:107], v209 offset:34816
	s_waitcnt lgkmcnt(6)
	v_mfma_f32_32x32x16_bf16 v[80:95], v[196:199], v[148:151], v[80:95]
	v_exp_f32_e32 v192, v110
	v_exp_f32_e32 v194, v111
	ds_read_b128 v[108:111], v209 offset:39424
	s_waitcnt lgkmcnt(6)
	v_mfma_f32_32x32x16_bf16 v[80:95], v[2:5], v[168:171], v[80:95]
	v_cvt_pk_bf16_f32 v2, v206, v207
	v_cvt_pk_bf16_f32 v3, v15, v183
	v_cvt_pk_bf16_f32 v4, v14, v182
	v_cvt_pk_bf16_f32 v5, v203, v205
	ds_read_b128 v[182:185], v209 offset:25632
	s_waitcnt lgkmcnt(6)
	v_mfma_f32_32x32x16_bf16 v[80:95], v[6:9], v[156:159], v[80:95]
	v_cvt_pk_bf16_f32 v6, v202, v204
	v_cvt_pk_bf16_f32 v7, v187, v189
	v_cvt_pk_bf16_f32 v8, v186, v188
	ds_read_b128 v[186:189], v209 offset:30240
	s_waitcnt lgkmcnt(6)
	v_mfma_f32_32x32x16_bf16 v[80:95], v[10:13], v[176:179], v[80:95]
	s_waitcnt lgkmcnt(5)
	v_mfma_f32_32x32x16_bf16 v[64:79], v[96:99], v[2:5], v[64:79]
	ds_read_b128 v[10:13], v209 offset:34848
	s_waitcnt lgkmcnt(5)
	v_mfma_f32_32x32x16_bf16 v[48:63], v[100:103], v[2:5], v[48:63]
	s_nop 6
	v_exp_f32_e32 v195, v80
	v_exp_f32_e32 v193, v81
	ds_read_b128 v[96:99], v209 offset:39456
	v_exp_f32_e32 v191, v82
	v_cvt_pk_bf16_f32 v9, v192, v194
	v_pk_add_f32 v[14:15], v[194:195], v[192:193]
	s_nop 0
	v_pk_add_f32 v[14:15], v[190:191], v[14:15]
	s_waitcnt lgkmcnt(5)
	v_mfma_f32_32x32x16_bf16 v[32:47], v[104:107], v[2:5], v[32:47]
	ds_read_b128 v[100:103], v209 offset:25664
	v_exp_f32_e32 v0, v83
	v_exp_f32_e32 v190, v84
	v_exp_f32_e32 v105, v85
	v_add_f32_e32 v107, v0, v190
	s_waitcnt lgkmcnt(5)
	v_mfma_f32_32x32x16_bf16 v[16:31], v[108:111], v[2:5], v[16:31]
	ds_read_b128 v[80:83], v209 offset:30272
	v_exp_f32_e32 v106, v86
	v_exp_f32_e32 v104, v87
	s_nop 0
	v_pk_add_f32 v[108:109], v[104:105], v[106:107]
	s_waitcnt lgkmcnt(5)
	v_mfma_f32_32x32x16_bf16 v[64:79], v[182:185], v[6:9], v[64:79]
	ds_read_b128 v[2:5], v209 offset:34880
	v_exp_f32_e32 v111, v88
	v_exp_f32_e32 v185, v89
	s_waitcnt lgkmcnt(5)
	v_mfma_f32_32x32x16_bf16 v[48:63], v[186:189], v[6:9], v[48:63]
	v_exp_f32_e32 v110, v90
	v_exp_f32_e32 v184, v91
	ds_read_b128 v[84:87], v209 offset:39488
	v_pk_add_f32 v[182:183], v[184:185], v[110:111]
	s_waitcnt lgkmcnt(5)
	v_mfma_f32_32x32x16_bf16 v[32:47], v[10:13], v[6:9], v[32:47]
	s_barrier
	ds_read_b128 v[88:91], v209 offset:25696
	v_exp_f32_e32 v187, v92
	v_exp_f32_e32 v189, v93
	s_waitcnt lgkmcnt(5)
	v_mfma_f32_32x32x16_bf16 v[16:31], v[96:99], v[6:9], v[16:31]
	v_exp_f32_e32 v186, v94
	v_exp_f32_e32 v188, v95
	v_add_f32_e32 v92, v14, v15
	v_add_f32_e32 v92, v109, v92
	v_add_f32_e32 v6, v108, v92
	ds_read_b128 v[10:13], v209 offset:30304
	v_add_f32_e32 v6, v183, v6
	v_pk_add_f32 v[14:15], v[188:189], v[186:187]
	v_add_f32_e32 v6, v182, v6
	v_add_f32_e32 v6, v15, v6
	v_add_f32_e32 v182, v14, v6
	v_cvt_pk_bf16_f32 v6, v195, v193
	v_cvt_pk_bf16_f32 v7, v191, v0
	v_cvt_pk_bf16_f32 v8, v190, v105
	v_cvt_pk_bf16_f32 v9, v106, v104
	v_cvt_pk_bf16_f32 v92, v111, v185
	v_cvt_pk_bf16_f32 v93, v110, v184
	v_cvt_pk_bf16_f32 v94, v187, v189
	v_cvt_pk_bf16_f32 v95, v186, v188
	s_waitcnt lgkmcnt(5)
	v_mfma_f32_32x32x16_bf16 v[64:79], v[100:103], v[6:9], v[64:79]
	ds_read_b128 v[96:99], v209 offset:34912
	s_waitcnt lgkmcnt(5)
	v_mfma_f32_32x32x16_bf16 v[48:63], v[80:83], v[6:9], v[48:63]
	ds_read_b128 v[100:103], v209 offset:39520
	s_waitcnt lgkmcnt(5)
	v_mfma_f32_32x32x16_bf16 v[32:47], v[2:5], v[6:9], v[32:47]
	s_waitcnt lgkmcnt(4)
	v_mfma_f32_32x32x16_bf16 v[16:31], v[84:87], v[6:9], v[16:31]
	s_waitcnt lgkmcnt(3)
	v_mfma_f32_32x32x16_bf16 v[64:79], v[88:91], v[92:95], v[64:79]
	s_waitcnt lgkmcnt(2)
	v_mfma_f32_32x32x16_bf16 v[48:63], v[10:13], v[92:95], v[48:63]
	s_waitcnt lgkmcnt(1)
	v_mfma_f32_32x32x16_bf16 v[32:47], v[96:99], v[92:95], v[32:47]
	s_waitcnt lgkmcnt(0)
	v_mfma_f32_32x32x16_bf16 v[16:31], v[100:103], v[92:95], v[16:31]

.LBB0_709:
	s_add_i32 s9, s10, 1
	s_cmp_gt_i32 s10, s1
	s_cbranch_scc1 .Lattn2_stage_only
	v_add3_u32 v0, s100, v180, v206
	ds_read_b128 v[2:5], v0
	ds_read_b128 v[6:9], v0 offset:32
	ds_read_b128 v[10:13], v0 offset:64
	ds_read_b128 v[184:187], v0 offset:96
	ds_read_b128 v[188:191], v0 offset:128
	ds_read_b128 v[192:195], v0 offset:160
	ds_read_b128 v[196:199], v0 offset:192
	s_mov_b32 s11, s101
	v_add_u32_e32 v247, s11, v227
	v_add_u32_e32 v248, s11, v228
	v_add_u32_e32 v249, s11, v229
	v_add_u32_e32 v250, s11, v200
	v_add_u32_e32 v251, s11, v202
	s_cmp_lt_u32 s10, s7
	s_cselect_b64 s[16:17], -1, 0
	s_cmp_lg_u64 s[16:17], 0
	s_addc_u32 s6, s6, 0
	s_mov_b32 s22, s14
	s_mov_b32 s23, s15
	s_mov_b32 s26, s14
	s_mov_b32 s27, s15
	v_mov_b32_e32 v80, v213
	v_mov_b32_e32 v81, v80
	v_mov_b32_e32 v82, v80
	v_mov_b32_e32 v83, v80
	v_mov_b32_e32 v84, v80
	v_mov_b32_e32 v85, v80
	v_mov_b32_e32 v86, v80
	v_mov_b32_e32 v87, v80
	v_mov_b32_e32 v88, v80
	v_mov_b32_e32 v89, v80
	v_mov_b32_e32 v90, v80
	v_mov_b32_e32 v91, v80
	v_mov_b32_e32 v92, v80
	v_mov_b32_e32 v93, v80
	v_mov_b32_e32 v94, v80
	v_mov_b32_e32 v95, v80
	s_mov_b32 s10, s100
	s_waitcnt lgkmcnt(6)
	v_mfma_f32_32x32x16_bf16 v[96:111], v[2:5], v[132:135], v[80:95]
	s_mul_i32 s11, s6, 0x6000
	s_waitcnt vmcnt(4)
	ds_write_b128 v247, v[112:115]
	buffer_load_dwordx4 v[112:115], v207, s[20:23], s11 offen
	ds_read_b128 v[2:5], v0 offset:224
	s_waitcnt lgkmcnt(6)
	v_mfma_f32_32x32x16_bf16 v[96:111], v[6:9], v[136:139], v[96:111]
	ds_read_b128 v[6:9], v0 offset:256
	s_waitcnt lgkmcnt(6)
	v_mfma_f32_32x32x16_bf16 v[96:111], v[10:13], v[140:143], v[96:111]
	s_add_i32 s16, s11, 0x2000
	s_waitcnt vmcnt(4)
	ds_write_b128 v248, v[116:119]
	buffer_load_dwordx4 v[116:119], v207, s[20:23], s16 offen
	ds_read_b128 v[10:13], v0 offset:288
	s_waitcnt lgkmcnt(6)
	v_mfma_f32_32x32x16_bf16 v[96:111], v[184:187], v[144:147], v[96:111]
	ds_read_b128 v[184:187], v0 offset:320
	s_waitcnt lgkmcnt(6)
	v_mfma_f32_32x32x16_bf16 v[96:111], v[188:191], v[148:151], v[96:111]
	s_addk_i32 s11, 0x4000
	s_waitcnt vmcnt(4)
	ds_write_b128 v249, v[120:123]
	buffer_load_dwordx4 v[120:123], v207, s[20:23], s11 offen
	ds_read_b128 v[188:191], v0 offset:352
	s_waitcnt lgkmcnt(6)
	v_mfma_f32_32x32x16_bf16 v[96:111], v[192:195], v[152:155], v[96:111]
	ds_read_b128 v[192:195], v0 offset:12800
	s_waitcnt lgkmcnt(6)
	v_mfma_f32_32x32x16_bf16 v[96:111], v[196:199], v[156:159], v[96:111]
	s_lshl_b32 s11, s6, 7
	s_waitcnt vmcnt(4)
	ds_write_b128 v250, v[124:127] offset:25600
	buffer_load_dwordx4 v[124:127], v209, s[24:27], s11 offen
	ds_read_b128 v[196:199], v0 offset:12832
	s_waitcnt lgkmcnt(6)
	v_mfma_f32_32x32x16_bf16 v[96:111], v[2:5], v[160:163], v[96:111]
	ds_read_b128 v[2:5], v0 offset:12864
	s_waitcnt lgkmcnt(6)
	v_mfma_f32_32x32x16_bf16 v[96:111], v[6:9], v[164:167], v[96:111]
	s_add_i32 s11, s11, 0x100000
	s_waitcnt vmcnt(4)
	ds_write_b128 v251, v[128:131] offset:25600
	buffer_load_dwordx4 v[128:131], v209, s[24:27], s11 offen
	ds_read_b128 v[6:9], v0 offset:12896
	s_waitcnt lgkmcnt(6)
	v_mfma_f32_32x32x16_bf16 v[96:111], v[10:13], v[172:175], v[96:111]
	ds_read_b128 v[10:13], v0 offset:12928
	s_waitcnt lgkmcnt(6)
	v_mfma_f32_32x32x16_bf16 v[96:111], v[184:187], v[168:171], v[96:111]
	ds_read_b128 v[184:187], v0 offset:12960
	s_waitcnt lgkmcnt(6)
	v_mfma_f32_32x32x16_bf16 v[96:111], v[188:191], v[176:179], v[96:111]
	ds_read_b128 v[188:191], v0 offset:12992
	s_waitcnt lgkmcnt(6)
	v_mfma_f32_32x32x16_bf16 v[80:95], v[192:195], v[132:135], v[80:95]
	s_nop 8
	v_exp_f32_e32 v203, v96
	v_exp_f32_e32 v208, v97
	ds_read_b128 v[192:195], v0 offset:13024
	s_waitcnt lgkmcnt(6)
	v_mfma_f32_32x32x16_bf16 v[80:95], v[196:199], v[136:139], v[80:95]
	v_add_f32_e32 v14, v208, v203
	v_add_f32_e32 v96, v182, v14
	ds_read_b128 v[196:199], v0 offset:13056
	s_waitcnt lgkmcnt(6)
	v_mfma_f32_32x32x16_bf16 v[80:95], v[2:5], v[140:143], v[80:95]
	v_exp_f32_e32 v15, v98
	v_exp_f32_e32 v183, v99
	v_exp_f32_e32 v14, v100
	v_exp_f32_e32 v182, v101
	ds_read_b128 v[2:5], v0 offset:13088
	s_waitcnt lgkmcnt(6)
	v_mfma_f32_32x32x16_bf16 v[80:95], v[6:9], v[144:147], v[80:95]
	v_add_f32_e64 v6, v182, v14
	v_add_f32_e64 v7, v183, v15
	v_add_f32_e32 v7, v7, v96
	v_add_f32_e32 v98, v6, v7
	ds_read_b128 v[6:9], v0 offset:13120
	s_waitcnt lgkmcnt(6)
	v_mfma_f32_32x32x16_bf16 v[80:95], v[10:13], v[148:151], v[80:95]
	v_exp_f32_e32 v231, v102
	v_exp_f32_e32 v233, v103
	v_exp_f32_e32 v230, v104
	v_exp_f32_e32 v232, v105
	ds_read_b128 v[10:13], v0 offset:13152
	s_waitcnt lgkmcnt(6)
	v_mfma_f32_32x32x16_bf16 v[80:95], v[184:187], v[152:155], v[80:95]
	v_add_f32_e64 v96, v232, v230
	v_add_f32_e64 v97, v233, v231
	v_add_f32_e32 v0, v97, v98
	v_add_f32_e32 v0, v96, v0
	v_add3_u32 v234, s10, v181, v206
	ds_read_b128 v[96:99], v234 offset:25600
	s_waitcnt lgkmcnt(6)
	v_mfma_f32_32x32x16_bf16 v[80:95], v[188:191], v[156:159], v[80:95]
	v_exp_f32_e32 v187, v106
	v_exp_f32_e32 v189, v107
	v_exp_f32_e32 v186, v108
	v_exp_f32_e32 v188, v109
	ds_read_b128 v[100:103], v234 offset:30208
	s_waitcnt lgkmcnt(6)
	v_mfma_f32_32x32x16_bf16 v[80:95], v[192:195], v[160:163], v[80:95]
	v_add_f32_e64 v104, v188, v186
	v_add_f32_e64 v105, v189, v187
	v_add_f32_e32 v0, v105, v0
	v_add_f32_e32 v190, v104, v0
	ds_read_b128 v[104:107], v234 offset:34816
	s_waitcnt lgkmcnt(6)
	v_mfma_f32_32x32x16_bf16 v[80:95], v[196:199], v[164:167], v[80:95]
	v_exp_f32_e32 v192, v110
	v_exp_f32_e32 v194, v111
	ds_read_b128 v[108:111], v234 offset:39424
	s_waitcnt lgkmcnt(6)
	v_mfma_f32_32x32x16_bf16 v[80:95], v[2:5], v[172:175], v[80:95]
	v_cvt_pk_bf16_f32 v2, v203, v208
	v_cvt_pk_bf16_f32 v3, v15, v183
	v_cvt_pk_bf16_f32 v4, v14, v182
	v_cvt_pk_bf16_f32 v5, v231, v233
	ds_read_b128 v[182:185], v234 offset:25632
	s_waitcnt lgkmcnt(6)
	v_mfma_f32_32x32x16_bf16 v[80:95], v[6:9], v[168:171], v[80:95]
	v_cvt_pk_bf16_f32 v6, v230, v232
	v_cvt_pk_bf16_f32 v7, v187, v189
	v_cvt_pk_bf16_f32 v8, v186, v188
	ds_read_b128 v[186:189], v234 offset:30240
	s_waitcnt lgkmcnt(6)
	v_mfma_f32_32x32x16_bf16 v[80:95], v[10:13], v[176:179], v[80:95]
	s_waitcnt lgkmcnt(5)
	v_mfma_f32_32x32x16_bf16 v[64:79], v[96:99], v[2:5], v[64:79]
	ds_read_b128 v[10:13], v234 offset:34848
	s_waitcnt lgkmcnt(5)
	v_mfma_f32_32x32x16_bf16 v[48:63], v[100:103], v[2:5], v[48:63]
	s_nop 6
	v_exp_f32_e32 v195, v80
	v_exp_f32_e32 v193, v81
	ds_read_b128 v[96:99], v234 offset:39456
	v_exp_f32_e32 v191, v82
	v_cvt_pk_bf16_f32 v9, v192, v194
	v_pk_add_f32 v[14:15], v[194:195], v[192:193]
	s_nop 0
	v_pk_add_f32 v[14:15], v[190:191], v[14:15]
	s_waitcnt lgkmcnt(5)
	v_mfma_f32_32x32x16_bf16 v[32:47], v[104:107], v[2:5], v[32:47]
	ds_read_b128 v[100:103], v234 offset:25664
	v_exp_f32_e32 v0, v83
	v_exp_f32_e32 v190, v84
	v_exp_f32_e32 v105, v85
	v_add_f32_e32 v107, v0, v190
	s_waitcnt lgkmcnt(5)
	v_mfma_f32_32x32x16_bf16 v[16:31], v[108:111], v[2:5], v[16:31]
	ds_read_b128 v[80:83], v234 offset:30272
	v_exp_f32_e32 v106, v86
	v_exp_f32_e32 v104, v87
	s_nop 0
	v_pk_add_f32 v[108:109], v[104:105], v[106:107]
	s_waitcnt lgkmcnt(5)
	v_mfma_f32_32x32x16_bf16 v[64:79], v[182:185], v[6:9], v[64:79]
	ds_read_b128 v[2:5], v234 offset:34880
	v_exp_f32_e32 v111, v88
	v_exp_f32_e32 v185, v89
	s_waitcnt lgkmcnt(5)
	v_mfma_f32_32x32x16_bf16 v[48:63], v[186:189], v[6:9], v[48:63]
	v_exp_f32_e32 v110, v90
	v_exp_f32_e32 v184, v91
	ds_read_b128 v[84:87], v234 offset:39488
	v_pk_add_f32 v[182:183], v[184:185], v[110:111]
	s_waitcnt lgkmcnt(5)
	v_mfma_f32_32x32x16_bf16 v[32:47], v[10:13], v[6:9], v[32:47]
	s_barrier
	ds_read_b128 v[88:91], v234 offset:25696
	v_exp_f32_e32 v187, v92
	v_exp_f32_e32 v189, v93
	s_waitcnt lgkmcnt(5)
	v_mfma_f32_32x32x16_bf16 v[16:31], v[96:99], v[6:9], v[16:31]
	v_exp_f32_e32 v186, v94
	v_exp_f32_e32 v188, v95
	v_add_f32_e32 v92, v14, v15
	v_add_f32_e32 v92, v109, v92
	v_add_f32_e32 v6, v108, v92
	ds_read_b128 v[10:13], v234 offset:30304
	v_add_f32_e32 v6, v183, v6
	v_pk_add_f32 v[14:15], v[188:189], v[186:187]
	v_add_f32_e32 v6, v182, v6
	v_add_f32_e32 v6, v15, v6
	v_add_f32_e32 v182, v14, v6
	v_cvt_pk_bf16_f32 v6, v195, v193
	v_cvt_pk_bf16_f32 v7, v191, v0
	v_cvt_pk_bf16_f32 v8, v190, v105
	v_cvt_pk_bf16_f32 v9, v106, v104
	v_cvt_pk_bf16_f32 v92, v111, v185
	v_cvt_pk_bf16_f32 v93, v110, v184
	v_cvt_pk_bf16_f32 v94, v187, v189
	v_cvt_pk_bf16_f32 v95, v186, v188
	s_waitcnt lgkmcnt(5)
	v_mfma_f32_32x32x16_bf16 v[64:79], v[100:103], v[6:9], v[64:79]
	ds_read_b128 v[96:99], v234 offset:34912
	s_waitcnt lgkmcnt(5)
	v_mfma_f32_32x32x16_bf16 v[48:63], v[80:83], v[6:9], v[48:63]
	ds_read_b128 v[100:103], v234 offset:39520
	s_waitcnt lgkmcnt(5)
	v_mfma_f32_32x32x16_bf16 v[32:47], v[2:5], v[6:9], v[32:47]
	s_waitcnt lgkmcnt(4)
	v_mfma_f32_32x32x16_bf16 v[16:31], v[84:87], v[6:9], v[16:31]
	s_waitcnt lgkmcnt(3)
	v_mfma_f32_32x32x16_bf16 v[64:79], v[88:91], v[92:95], v[64:79]
	s_waitcnt lgkmcnt(2)
	v_mfma_f32_32x32x16_bf16 v[48:63], v[10:13], v[92:95], v[48:63]
	s_waitcnt lgkmcnt(1)
	v_mfma_f32_32x32x16_bf16 v[32:47], v[96:99], v[92:95], v[32:47]
	s_waitcnt lgkmcnt(0)
	v_mfma_f32_32x32x16_bf16 v[16:31], v[100:103], v[92:95], v[16:31]
